# lever 7: xor 1/2/4/8 butterfly steps of the row-sum reductions (post_rows, norm_rows, final_norm) done with DPP adds instead of ds_bpermute round trips
# speedup vs baseline: 1.0062x; 1.0026x over previous
; __device__ __forceinline__ unsigned pk2(float lo, float hi) { f32x2 v = {lo, hi}; bf16x2_t b = __builtin_convertvector(v, bf16x2_t); return __builtin_bit_cast(unsigned, b); }
; __device__ __forceinline__ float bflo(unsigned w) { return __uint_as_float(w << 16); }
; __device__ __forceinline__ float bfhi(unsigned w) { return __uint_as_float(w & 0xffff0000u); }
; __device__ __forceinline__ float fexp2(float x) { return __builtin_amdgcn_exp2f(x); }
; __device__ __forceinline__ float frcp(float x) { return __builtin_amdgcn_rcpf(x); }
; __device__ __forceinline__ void post_rows(const bf16_t* OP, const float* LSE, const bf16_t* zC, bf16_t* yb, bf16_t* yc, const float* hnorm, int tid, int bid, int nbk) {
;     ...
;             const int hb = lane >> 3;
;             const float l0 = LSE[((size_t)0 * MH + r) * 8 + hb], l1 = LSE[((size_t)1 * MH + r) * 8 + hb], l2 = LSE[((size_t)2 * MH + r) * 8 + hb];
;             const float mx = fmaxf(l0, fmaxf(l1, l2));
;             float w0 = fexp2(l0 - mx), w1 = fexp2(l1 - mx), w2 = fexp2(l2 - mx);
;             const float iw = frcp(w0 + w1 + w2); w0 *= iw; w1 *= iw; w2 *= iw;
;             const u32x4 a = *(const u32x4*)(OP + ((size_t)0 * MH + r) * 512 + lane * 8), b = *(const u32x4*)(OP + ((size_t)1 * MH + r) * 512 + lane * 8), c = *(const u32x4*)(OP + ((size_t)2 * MH + r) * 512 + lane * 8);
;             u32x4 o;
;             o.x = pk2(w0 * bflo(a.x) + w1 * bflo(b.x) + w2 * bflo(c.x), w0 * bfhi(a.x) + w1 * bfhi(b.x) + w2 * bfhi(c.x));
;             o.y = pk2(w0 * bflo(a.y) + w1 * bflo(b.y) + w2 * bflo(c.y), w0 * bfhi(a.y) + w1 * bfhi(b.y) + w2 * bfhi(c.y));
;             o.z = pk2(w0 * bflo(a.z) + w1 * bflo(b.z) + w2 * bflo(c.z), w0 * bfhi(a.z) + w1 * bfhi(b.z) + w2 * bfhi(c.z));
;             o.w = pk2(w0 * bflo(a.w) + w1 * bflo(b.w) + w2 * bflo(c.w), w0 * bfhi(a.w) + w1 * bfhi(b.w) + w2 * bfhi(c.w));
;             *(u32x4*)(yb + (size_t)r * 1536 + lane * 8) = o;
.LBB0_154:
	v_lshl_add_u64 v[4:5], s[60:61], 0, v[14:15]
	v_add_co_u32_e32 v6, vcc, 0x1e800000, v4
	v_lshl_add_u64 v[24:25], s[60:61], 0, v[12:13]
	v_addc_co_u32_e32 v7, vcc, 0, v5, vcc
	v_add_co_u32_e32 v6, vcc, 0x1e880000, v4
	s_mov_b32 s14, 0x1b800000
	s_nop 0
	v_addc_co_u32_e32 v7, vcc, 0, v5, vcc
	v_add_co_u32_e32 v4, vcc, 0x1e900000, v4
	s_nop 0
	v_addc_co_u32_e32 v5, vcc, 0, v5, vcc
	v_add_u32_e32 v3, s46, v3
	v_lshl_add_u64 v[12:13], v[12:13], 0, s[52:53]
	v_lshl_add_u64 v[14:15], v[14:15], 0, s[54:55]
	s_waitcnt vmcnt(6)
	v_mov_b32_e32 v20, v188
	v_mov_b32_e32 v6, v189
	v_mov_b32_e32 v4, v190
	v_max3_f32 v5, v20, v6, v4
	v_sub_f32_e32 v7, v20, v5
	v_sub_f32_e32 v6, v6, v5
	v_exp_f32_e32 v29, v7
	v_exp_f32_e32 v28, v6
	v_sub_f32_e32 v4, v4, v5
	v_exp_f32_e32 v4, v4
	v_add_f32_e32 v5, v29, v28
	v_add_f32_e32 v5, v4, v5
	v_rcp_f32_e32 v30, v5
	s_nop 0
	v_mul_f32_e32 v32, v4, v30
	v_add_co_u32_e32 v4, vcc, s14, v24
	s_mov_b32 s14, 0x1c800000
	s_nop 0
	v_addc_co_u32_e32 v5, vcc, 0, v25, vcc
	v_add_co_u32_e32 v20, vcc, s14, v24
	s_mov_b32 s14, 0x1d800000
	s_nop 0
	v_addc_co_u32_e32 v21, vcc, 0, v25, vcc
	s_waitcnt vmcnt(3)
	v_mov_b32_e32 v4, v192
	v_mov_b32_e32 v5, v193
	v_mov_b32_e32 v6, v194
	v_mov_b32_e32 v7, v195
	v_add_co_u32_e32 v24, vcc, s14, v24
	v_mov_b32_e32 v20, v196
	v_mov_b32_e32 v21, v197
	v_mov_b32_e32 v22, v198
	v_mov_b32_e32 v23, v199
	s_nop 0
	v_addc_co_u32_e32 v25, vcc, 0, v25, vcc
	v_mov_b32_e32 v24, v200
	v_mov_b32_e32 v25, v201
	v_mov_b32_e32 v26, v202
	v_mov_b32_e32 v27, v203
	v_pk_mul_f32 v[28:29], v[28:29], v[30:31] op_sel_hi:[1,0]
	s_mov_b32 s14, 0x18800000
	v_lshlrev_b32_e32 v34, 16, v4
	v_and_b32_e32 v31, 0xffff0000, v4
	v_and_b32_e32 v35, 0xffff0000, v20
	v_lshlrev_b32_e32 v30, 16, v20
	v_pk_mul_f32 v[34:35], v[28:29], v[34:35] op_sel:[1,0] op_sel_hi:[0,1]
	v_lshlrev_b32_e32 v36, 16, v24
	v_and_b32_e32 v37, 0xffff0000, v24
	v_pk_fma_f32 v[30:31], v[28:29], v[30:31], v[34:35]
	v_lshlrev_b32_e32 v20, 16, v5
	v_pk_fma_f32 v[30:31], v[32:33], v[36:37], v[30:31] op_sel_hi:[0,1,1]
	v_cvt_pk_bf16_f32 v4, v30, v31
	v_lshlrev_b32_e32 v30, 16, v21
	v_and_b32_e32 v21, 0xffff0000, v21
	v_and_b32_e32 v31, 0xffff0000, v5
	v_pk_mul_f32 v[20:21], v[28:29], v[20:21] op_sel:[1,0] op_sel_hi:[0,1]
	v_lshlrev_b32_e32 v24, 16, v25
	v_and_b32_e32 v25, 0xffff0000, v25
	v_pk_fma_f32 v[20:21], v[28:29], v[30:31], v[20:21]
	v_lshlrev_b32_e32 v30, 16, v26
	v_pk_fma_f32 v[20:21], v[32:33], v[24:25], v[20:21] op_sel_hi:[0,1,1]
	v_lshlrev_b32_e32 v24, 16, v6
	v_and_b32_e32 v25, 0xffff0000, v22
	v_cvt_pk_bf16_f32 v5, v20, v21
	v_lshlrev_b32_e32 v20, 16, v22
	v_and_b32_e32 v21, 0xffff0000, v6
	v_pk_mul_f32 v[24:25], v[28:29], v[24:25] op_sel:[1,0] op_sel_hi:[0,1]
	v_and_b32_e32 v31, 0xffff0000, v26
	v_pk_fma_f32 v[20:21], v[28:29], v[20:21], v[24:25]
	v_lshlrev_b32_e32 v22, 16, v7
	v_pk_fma_f32 v[20:21], v[32:33], v[30:31], v[20:21] op_sel_hi:[0,1,1]
	v_cvt_pk_bf16_f32 v6, v20, v21
	v_lshlrev_b32_e32 v20, 16, v23
	v_and_b32_e32 v23, 0xffff0000, v23
	v_and_b32_e32 v21, 0xffff0000, v7
	v_pk_mul_f32 v[22:23], v[28:29], v[22:23] op_sel:[1,0] op_sel_hi:[0,1]
	v_pk_fma_f32 v[20:21], v[28:29], v[20:21], v[22:23]
	v_lshlrev_b32_e32 v22, 16, v27
	v_and_b32_e32 v23, 0xffff0000, v27
	v_pk_fma_f32 v[20:21], v[32:33], v[22:23], v[20:21] op_sel_hi:[0,1,1]
	v_cvt_pk_bf16_f32 v7, v20, v21
	v_lshl_add_u64 v[20:21], s[60:61], 0, v[10:11]
	v_add_co_u32_e32 v34, vcc, s14, v20
	v_lshl_add_u64 v[24:25], s[60:61], 0, v[8:9]
	s_nop 0
	v_addc_co_u32_e32 v35, vcc, 0, v21, vcc
	s_mov_b32 s14, 0xd800000
	v_add_co_u32_e32 v20, vcc, s14, v24
	s_mov_b32 s14, 0xd801000
	s_nop 0
	v_addc_co_u32_e32 v21, vcc, 0, v25, vcc
	global_store_dwordx4 v[34:35], v[4:7], off offset:1024
	v_add_co_u32_e32 v24, vcc, s14, v24
	s_nop 1
	s_waitcnt vmcnt(1)
; __device__ __forceinline__ unsigned pk2(float lo, float hi) { f32x2 v = {lo, hi}; bf16x2_t b = __builtin_convertvector(v, bf16x2_t); return __builtin_bit_cast(unsigned, b); }
; __device__ __forceinline__ float bflo(unsigned w) { return __uint_as_float(w << 16); }
; __device__ __forceinline__ float bfhi(unsigned w) { return __uint_as_float(w & 0xffff0000u); }
; __device__ __forceinline__ float siluf_(float x) { return x * frcp(1.f + fexp2(-LOG2E * x)); }
; __device__ __forceinline__ void post_rows(const bf16_t* OP, const float* LSE, const bf16_t* zC, bf16_t* yb, bf16_t* yc, const float* hnorm, int tid, int bid, int nbk) {
;     ...
;             const bf16_t* zr = zC + (size_t)r * 2560 + lane * 8;
;             const u32x4 a = *(const u32x4*)(zr + 512), b = *(const u32x4*)(zr + 1024), g = *(const u32x4*)(zr + 2048);
;             float s[8], og[8];
;             s[0] = bflo(a.x) + bflo(b.x); s[1] = bfhi(a.x) + bfhi(b.x); s[2] = bflo(a.y) + bflo(b.y); s[3] = bfhi(a.y) + bfhi(b.y);
;             s[4] = bflo(a.z) + bflo(b.z); s[5] = bfhi(a.z) + bfhi(b.z); s[6] = bflo(a.w) + bflo(b.w); s[7] = bfhi(a.w) + bfhi(b.w);
;             og[0] = bflo(g.x); og[1] = bfhi(g.x); og[2] = bflo(g.y); og[3] = bfhi(g.y); og[4] = bflo(g.z); og[5] = bfhi(g.z); og[6] = bflo(g.w); og[7] = bfhi(g.w);
;             float ss = 0.f;
; #pragma unroll
;             for (int i = 0; i < 8; ++i) ss += s[i] * s[i];
;             ss += __shfl_xor(ss, 1); ss += __shfl_xor(ss, 2); ss += __shfl_xor(ss, 4); ss += __shfl_xor(ss, 8);
;             const float rn = 1.0f / sqrtf(ss * (1.f / 128.f) + 1e-6f);
;             const float* gn = hnorm + (lane & 15) * 8;
;             float y[8];
; #pragma unroll
;             for (int i = 0; i < 8; ++i) y[i] = s[i] * rn * gn[i] * siluf_(og[i]);
;             u32x4 o; o.x = pk2(y[0], y[1]); o.y = pk2(y[2], y[3]); o.z = pk2(y[4], y[5]); o.w = pk2(y[6], y[7]);
;             *(u32x4*)(yc + (size_t)r * 1536 + lane * 8) = o;
	v_mov_b32_e32 v4, v204
	v_mov_b32_e32 v5, v205
	v_mov_b32_e32 v6, v206
	v_mov_b32_e32 v7, v207
	s_nop 0
	v_mov_b32_e32 v20, v208
	v_mov_b32_e32 v21, v209
	v_mov_b32_e32 v22, v210
	v_mov_b32_e32 v23, v211
	v_addc_co_u32_e32 v25, vcc, 0, v25, vcc
	v_mov_b32_e32 v24, v212
	v_mov_b32_e32 v25, v213
	v_mov_b32_e32 v26, v214
	v_mov_b32_e32 v27, v215
	v_lshl_add_u64 v[8:9], v[8:9], 0, s[48:49]
	v_lshl_add_u64 v[10:11], v[10:11], 0, s[50:51]
	v_lshl_add_u64 v[224:225], s[60:61], 0, v[14:15]
	v_lshl_add_u64 v[226:227], s[60:61], 0, v[12:13]
	v_lshl_add_u64 v[228:229], s[60:61], 0, v[8:9]
	v_add_co_u32_e32 v230, vcc, 0x1e800000, v224
	s_nop 1
	v_addc_co_u32_e32 v231, vcc, 0, v225, vcc
	v_add_co_u32_e32 v232, vcc, 0x1e880000, v224
	s_nop 1
	v_addc_co_u32_e32 v233, vcc, 0, v225, vcc
	v_add_co_u32_e32 v234, vcc, 0x1e900000, v224
	s_nop 1
	v_addc_co_u32_e32 v235, vcc, 0, v225, vcc
	global_load_dword v188, v[230:231], off
	global_load_dword v189, v[232:233], off
	global_load_dword v190, v[234:235], off
	v_add_co_u32_e32 v230, vcc, 0x1b800000, v226
	s_nop 1
	v_addc_co_u32_e32 v231, vcc, 0, v227, vcc
	v_add_co_u32_e32 v232, vcc, 0x1c800000, v226
	s_nop 1
	v_addc_co_u32_e32 v233, vcc, 0, v227, vcc
	v_add_co_u32_e32 v234, vcc, 0x1d800000, v226
	s_nop 1
	v_addc_co_u32_e32 v235, vcc, 0, v227, vcc
	global_load_dwordx4 v[192:195], v[230:231], off
	global_load_dwordx4 v[196:199], v[232:233], off
	global_load_dwordx4 v[200:203], v[234:235], off
	v_add_co_u32_e32 v230, vcc, 0xd800000, v228
	s_nop 1
	v_addc_co_u32_e32 v231, vcc, 0, v229, vcc
	v_add_co_u32_e32 v232, vcc, 0xd801000, v228
	s_nop 1
	v_addc_co_u32_e32 v233, vcc, 0, v229, vcc
	global_load_dwordx4 v[204:207], v[230:231], off offset:1024
	global_load_dwordx4 v[208:211], v[230:231], off offset:2048
	global_load_dwordx4 v[212:215], v[232:233], off
	v_lshlrev_b32_e32 v28, 16, v7
	v_and_b32_e32 v29, 0xffff0000, v7
	v_lshlrev_b32_e32 v30, 16, v23
	v_and_b32_e32 v31, 0xffff0000, v23
	v_pk_add_f32 v[36:37], v[28:29], v[30:31]
	v_lshlrev_b32_e32 v28, 16, v6
	v_and_b32_e32 v29, 0xffff0000, v6
	v_lshlrev_b32_e32 v6, 16, v22
	v_and_b32_e32 v7, 0xffff0000, v22
	v_lshlrev_b32_e32 v22, 16, v26
	v_and_b32_e32 v23, 0xffff0000, v26
	v_mul_f32_e32 v26, 0xbfb8aa3b, v22
	v_mul_f32_e32 v45, 0xbfb8aa3b, v23
	v_exp_f32_e32 v26, v26
	v_exp_f32_e32 v45, v45
	v_lshlrev_b32_e32 v46, 16, v21
	v_and_b32_e32 v47, 0xffff0000, v21
	v_add_f32_e32 v26, 1.0, v26
	v_add_f32_e32 v45, 1.0, v45
	v_rcp_f32_e32 v44, v26
	v_rcp_f32_e32 v45, v45
	v_lshlrev_b32_e32 v38, 16, v27
	v_and_b32_e32 v39, 0xffff0000, v27
	v_pk_add_f32 v[6:7], v[28:29], v[6:7]
	v_pk_mul_f32 v[22:23], v[44:45], v[22:23]
	v_lshlrev_b32_e32 v44, 16, v5
	v_and_b32_e32 v45, 0xffff0000, v5
	v_pk_add_f32 v[44:45], v[44:45], v[46:47]
	v_lshlrev_b32_e32 v46, 16, v25
	v_mul_f32_e32 v5, 0xbfb8aa3b, v46
	v_mov_b32_e32 v26, v216
	v_mov_b32_e32 v27, v217
	v_mov_b32_e32 v28, v218
	v_mov_b32_e32 v29, v219
	v_mov_b32_e32 v30, v220
	v_mov_b32_e32 v31, v221
	v_mov_b32_e32 v32, v222
	v_mov_b32_e32 v33, v223
	v_exp_f32_e32 v5, v5
	v_and_b32_e32 v47, 0xffff0000, v25
	v_and_b32_e32 v21, 0xffff0000, v24
	v_pk_mul_f32 v[48:49], v[44:45], v[44:45]
	v_add_f32_e32 v5, 1.0, v5
	v_rcp_f32_e32 v50, v5
	v_mul_f32_e32 v5, 0xbfb8aa3b, v47
	v_exp_f32_e32 v5, v5
	v_pk_mul_f32 v[42:43], v[6:7], v[6:7]
	v_pk_mul_f32 v[40:41], v[36:37], v[36:37]
	v_add_f32_e32 v5, 1.0, v5
	v_rcp_f32_e32 v51, v5
	v_and_b32_e32 v5, 0xffff0000, v20
	v_pk_mul_f32 v[46:47], v[50:51], v[46:47]
	v_lshlrev_b32_e32 v50, 16, v4
	v_and_b32_e32 v51, 0xffff0000, v4
	v_lshlrev_b32_e32 v4, 16, v20
	v_pk_add_f32 v[4:5], v[50:51], v[4:5]
	v_lshlrev_b32_e32 v20, 16, v24
	v_pk_mul_f32 v[24:25], v[4:5], v[4:5]
	v_mul_f32_e32 v50, 0xbfb8aa3b, v20
	v_add_f32_e32 v24, v24, v25
	v_add_f32_e32 v24, v48, v24
	v_add_f32_e32 v24, v49, v24
	v_add_f32_e32 v24, v42, v24
	v_add_f32_e32 v24, v43, v24
	v_add_f32_e32 v24, v40, v24
	v_add_f32_e32 v24, v41, v24
	v_mul_f32_e32 v51, 0xbfb8aa3b, v21
	v_exp_f32_e32 v50, v50
	v_exp_f32_e32 v51, v51
	s_waitcnt lgkmcnt(0)
	s_nop 1
	v_add_f32_dpp v24, v24, v24 quad_perm:[1,0,3,2] row_mask:0xf bank_mask:0xf
	v_add_f32_e32 v50, 1.0, v50
	v_add_f32_e32 v51, 1.0, v51
	v_rcp_f32_e32 v50, v50
	v_rcp_f32_e32 v51, v51
	s_waitcnt lgkmcnt(0)
	s_nop 1
	v_add_f32_dpp v24, v24, v24 quad_perm:[2,3,0,1] row_mask:0xf bank_mask:0xf
	v_pk_mul_f32 v[20:21], v[50:51], v[20:21]
	s_waitcnt lgkmcnt(0)
	s_nop 1
	v_add_f32_dpp v24, v24, v24 row_half_mirror row_mask:0xf bank_mask:0xf
	s_waitcnt lgkmcnt(0)
	s_nop 1
	v_add_f32_dpp v24, v24, v24 row_mirror row_mask:0xf bank_mask:0xf
	v_fmamk_f32 v24, v24, 0x3c000000, v175
	v_cmp_gt_f32_e32 vcc, s33, v24
	v_mul_f32_e32 v25, 0x4f800000, v24
	s_nop 0
	v_cndmask_b32_e32 v24, v24, v25, vcc
	v_sqrt_f32_e32 v25, v24
	s_nop 0
	v_add_u32_e32 v40, -1, v25
	v_fma_f32 v41, -v40, v25, v24
	v_cmp_ge_f32_e64 s[40:41], 0, v41
	v_add_u32_e32 v41, 1, v25
	s_nop 0
	v_cndmask_b32_e64 v40, v25, v40, s[40:41]
	v_fma_f32 v25, -v41, v25, v24
	v_cmp_lt_f32_e64 s[40:41], 0, v25
	s_nop 1
	v_cndmask_b32_e64 v25, v40, v41, s[40:41]
	v_mul_f32_e32 v40, 0x37800000, v25
	v_cndmask_b32_e32 v25, v25, v40, vcc
	v_cmp_class_f32_e32 vcc, v24, v180
	s_nop 1
	v_cndmask_b32_e32 v24, v25, v24, vcc
	v_div_scale_f32 v25, s[14:15], v24, v24, 1.0
	v_rcp_f32_e32 v40, v25
	s_movk_i32 s14, 0x3fff
	v_fma_f32 v41, -v25, v40, 1.0
	v_fmac_f32_e32 v40, v41, v40
	v_div_scale_f32 v41, vcc, 1.0, v24, 1.0
	v_mul_f32_e32 v42, v41, v40
	v_fma_f32 v43, -v25, v42, v41
	v_fmac_f32_e32 v42, v43, v40
	v_fma_f32 v25, -v25, v42, v41
	v_div_fmas_f32 v25, v25, v40, v42
	v_div_fixup_f32 v24, v25, v24, 1.0
	v_pk_mul_f32 v[6:7], v[6:7], v[24:25] op_sel_hi:[1,0]
	v_pk_mul_f32 v[4:5], v[4:5], v[24:25] op_sel_hi:[1,0]
	v_pk_mul_f32 v[6:7], v[26:27], v[6:7]
	v_pk_mul_f32 v[4:5], v[30:31], v[4:5]
	v_pk_mul_f32 v[6:7], v[22:23], v[6:7]
	v_mul_f32_e32 v22, 0xbfb8aa3b, v38
	v_mul_f32_e32 v23, 0xbfb8aa3b, v39
	v_exp_f32_e32 v22, v22
	v_exp_f32_e32 v23, v23
	v_pk_mul_f32 v[4:5], v[20:21], v[4:5]
	v_pk_mul_f32 v[20:21], v[44:45], v[24:25] op_sel_hi:[1,0]
	v_add_f32_e32 v22, 1.0, v22
	v_add_f32_e32 v23, 1.0, v23
	v_rcp_f32_e32 v22, v22
	v_rcp_f32_e32 v23, v23
	v_pk_mul_f32 v[24:25], v[36:37], v[24:25] op_sel_hi:[1,0]
	v_pk_mul_f32 v[20:21], v[32:33], v[20:21]
	v_pk_mul_f32 v[24:25], v[28:29], v[24:25]
	v_pk_mul_f32 v[22:23], v[22:23], v[38:39]
	v_pk_mul_f32 v[20:21], v[46:47], v[20:21]
	v_pk_mul_f32 v[22:23], v[22:23], v[24:25]
	v_cmp_lt_i32_e32 vcc, s14, v3
	v_cvt_pk_bf16_f32 v4, v4, v5
	v_cvt_pk_bf16_f32 v5, v20, v21
	v_cvt_pk_bf16_f32 v6, v6, v7
	v_cvt_pk_bf16_f32 v7, v22, v23
	s_or_b64 s[56:57], vcc, s[56:57]
	global_store_dwordx4 v[34:35], v[4:7], off offset:2048
	s_andn2_b64 exec, exec, s[56:57]
	s_cbranch_execnz .LBB0_154

; __device__ __forceinline__ void norm_rows(const float* src, bf16_t* xn, float* outf, const float* gain, unsigned* rs_out, int tid, int bid, int nbk) {
;     ...
;     for (int m = gw; m < MTOK; m += NGW) {
;         const float* xr = src + (size_t)m * DM + lane * 8;
;         f32x4 v[4]; float s = 0.f;
; #pragma unroll
;         for (int j = 0; j < 4; ++j) { v[j] = *(const f32x4*)(xr + (j >> 1) * 512 + (j & 1) * 4); s += (v[j][0] * v[j][0] + v[j][1] * v[j][1]) + (v[j][2] * v[j][2] + v[j][3] * v[j][3]); }
;         const float tot = wave_sum(s);
;         if (rs_out && lane == 0) rs_out[m] = (unsigned)(tot * 1024.f + 0.5f);
.Lnr_body:
	v_mov_b32_e32 v8, v140
	v_mov_b32_e32 v9, v141
	v_mov_b32_e32 v10, v142
	v_mov_b32_e32 v11, v143
	v_mov_b32_e32 v4, v144
	v_mov_b32_e32 v5, v145
	v_mov_b32_e32 v6, v146
	v_mov_b32_e32 v7, v147
	v_mov_b32_e32 v16, v148
	v_mov_b32_e32 v17, v149
	v_mov_b32_e32 v18, v150
	v_mov_b32_e32 v19, v151
	v_mov_b32_e32 v12, v152
	v_mov_b32_e32 v13, v153
	v_mov_b32_e32 v14, v154
	v_mov_b32_e32 v15, v155
	v_add_u32_e32 v138, s44, v3
	v_cmp_ge_i32_e64 s[100:101], s67, v138
	s_and_saveexec_b64 s[100:101], s[100:101]
	v_lshl_add_u64 v[138:139], v[22:23], 0, s[48:49]
	global_load_dwordx4 v[140:143], v[138:139], off
	global_load_dwordx4 v[144:147], v[138:139], off offset:16
	global_load_dwordx4 v[148:151], v[138:139], off offset:2048
	global_load_dwordx4 v[152:155], v[138:139], off offset:2064
	s_mov_b64 exec, s[100:101]
	v_mul_f32_e32 v30, v9, v9
	s_waitcnt lgkmcnt(0)
	v_mul_f32_e32 v31, v11, v11
	v_mul_f32_e32 v32, v5, v5
	v_mul_f32_e32 v33, v7, v7
	v_mul_f32_e32 v34, v17, v17
	v_mul_f32_e32 v35, v19, v19
	v_fmac_f32_e32 v30, v8, v8
	v_fmac_f32_e32 v31, v10, v10
	v_fmac_f32_e32 v32, v4, v4
	v_fmac_f32_e32 v33, v6, v6
	v_mul_f32_e32 v36, v13, v13
	v_mul_f32_e32 v37, v15, v15
	v_fmac_f32_e32 v34, v16, v16
	v_fmac_f32_e32 v35, v18, v18
	v_add_f32_e32 v30, v30, v31
	v_add_f32_e32 v31, v32, v33
	v_fmac_f32_e32 v36, v12, v12
	v_fmac_f32_e32 v37, v14, v14
	v_add_f32_e32 v32, v34, v35
	v_add_f32_e32 v30, v30, v31
	v_add_f32_e32 v30, v30, v32
	v_add_f32_e32 v31, v36, v37
	v_add_f32_e32 v30, v30, v31
	s_waitcnt lgkmcnt(0)
	s_nop 1
	v_add_f32_dpp v30, v30, v30 quad_perm:[1,0,3,2] row_mask:0xf bank_mask:0xf
	s_waitcnt lgkmcnt(0)
	s_nop 1
	v_add_f32_dpp v30, v30, v30 quad_perm:[2,3,0,1] row_mask:0xf bank_mask:0xf
	s_waitcnt lgkmcnt(0)
	s_nop 1
	v_add_f32_dpp v30, v30, v30 row_half_mirror row_mask:0xf bank_mask:0xf
	s_waitcnt lgkmcnt(0)
	s_nop 1
	v_add_f32_dpp v30, v30, v30 row_mirror row_mask:0xf bank_mask:0xf
	ds_bpermute_b32 v31, v28, v30
	s_waitcnt lgkmcnt(0)
	v_add_f32_e32 v30, v30, v31
	ds_bpermute_b32 v31, v29, v30
	s_and_saveexec_b64 s[40:41], vcc
	s_cbranch_execz .LBB0_541
	s_waitcnt lgkmcnt(0)
	v_add_f32_e32 v30, v30, v31
	v_fma_f32 v30, v30, s3, 0.5
	v_cvt_u32_f32_e32 v30, v30
	global_store_dword v[0:1], v30, off
	s_branch .LBB0_541

; __device__ __forceinline__ float bflo(unsigned w) { return __uint_as_float(w << 16); }
; __device__ __forceinline__ float bfhi(unsigned w) { return __uint_as_float(w & 0xffff0000u); }
; __device__ __forceinline__ void final_norm_rows(const bf16_t* xb, float* outf, const float* gain, int tid, int bid, int nbk) {
;     ...
;     for (int m = gw; m < MTOK; m += NGW) {
;         const bf16_t* xr = xb + (size_t)m * DM + lane * 8;
;         const u32x4 a = *(const u32x4*)xr, b = *(const u32x4*)(xr + 512);
;         float v[16];
;         v[0] = bflo(a.x); v[1] = bfhi(a.x); v[2] = bflo(a.y); v[3] = bfhi(a.y); v[4] = bflo(a.z); v[5] = bfhi(a.z); v[6] = bflo(a.w); v[7] = bfhi(a.w);
;         v[8] = bflo(b.x); v[9] = bfhi(b.x); v[10] = bflo(b.y); v[11] = bfhi(b.y); v[12] = bflo(b.z); v[13] = bfhi(b.z); v[14] = bflo(b.w); v[15] = bfhi(b.w);
;         float s = 0.f;
; #pragma unroll
;         for (int i = 0; i < 16; ++i) s += v[i] * v[i];
;         const float r = 1.0f / sqrtf(wave_sum(s) * (1.f / DM) + 1e-6f);
;         float* o = outf + (size_t)m * DM + lane * 8; const float* g = gain + lane * 8;
; #pragma unroll
;         for (int hh = 0; hh < 2; ++hh)
; #pragma unroll
;             for (int q = 0; q < 2; ++q) { const f32x4 gg = *(const f32x4*)(g + hh * 512 + q * 4); f32x4 ov; ov[0] = v[hh * 8 + q * 4 + 0] * r * gg[0]; ov[1] = v[hh * 8 + q * 4 + 1] * r * gg[1]; ov[2] = v[hh * 8 + q * 4 + 2] * r * gg[2]; ov[3] = v[hh * 8 + q * 4 + 3] * r * gg[3]; *(f32x4*)(o + hh * 512 + q * 4) = ov; }
.LBB0_547:
	s_waitcnt vmcnt(4)
	v_mov_b32_e32 v14, v204
	v_mov_b32_e32 v15, v205
	v_mov_b32_e32 v16, v206
	v_mov_b32_e32 v17, v207
	v_mov_b32_e32 v18, v208
	v_mov_b32_e32 v19, v209
	v_mov_b32_e32 v20, v210
	v_mov_b32_e32 v21, v211
	v_mov_b32_e32 v22, v188
	v_mov_b32_e32 v23, v189
	v_mov_b32_e32 v24, v190
	v_mov_b32_e32 v25, v191
	v_add_u32_e32 v3, s44, v3
	v_lshl_add_u64 v[4:5], v[4:5], 0, s[0:1]
	global_load_dwordx4 v[204:207], v[4:5], off
	global_load_dwordx4 v[208:211], v[4:5], off offset:1024
	v_lshlrev_b32_e32 v28, 16, v14
	v_and_b32_e32 v29, 0xffff0000, v14
	v_and_b32_e32 v26, 0xffff0000, v21
	v_lshlrev_b32_e32 v27, 16, v21
	v_lshlrev_b32_e32 v14, 16, v15
	v_and_b32_e32 v15, 0xffff0000, v15
	v_lshlrev_b32_e32 v36, 16, v20
	v_and_b32_e32 v37, 0xffff0000, v20
	v_pk_mul_f32 v[20:21], v[28:29], v[28:29]
	v_pk_mul_f32 v[38:39], v[14:15], v[14:15]
	v_add_f32_e32 v20, v20, v21
	v_lshlrev_b32_e32 v30, 16, v16
	v_and_b32_e32 v31, 0xffff0000, v16
	v_add_f32_e32 v20, v38, v20
	v_pk_mul_f32 v[40:41], v[30:31], v[30:31]
	v_add_f32_e32 v20, v39, v20
	v_lshlrev_b32_e32 v32, 16, v17
	v_and_b32_e32 v33, 0xffff0000, v17
	v_add_f32_e32 v20, v40, v20
	v_pk_mul_f32 v[42:43], v[32:33], v[32:33]
	v_add_f32_e32 v20, v41, v20
	v_lshlrev_b32_e32 v34, 16, v18
	v_and_b32_e32 v35, 0xffff0000, v18
	v_add_f32_e32 v20, v42, v20
	v_pk_mul_f32 v[44:45], v[34:35], v[34:35]
	v_add_f32_e32 v20, v43, v20
	v_lshlrev_b32_e32 v18, 16, v19
	v_and_b32_e32 v19, 0xffff0000, v19
	v_add_f32_e32 v20, v44, v20
	v_pk_mul_f32 v[46:47], v[18:19], v[18:19]
	v_add_f32_e32 v20, v45, v20
	v_add_f32_e32 v20, v46, v20
	v_pk_mul_f32 v[48:49], v[36:37], v[36:37]
	v_add_f32_e32 v20, v47, v20
	v_add_f32_e32 v20, v48, v20
	v_pk_mul_f32 v[16:17], v[26:27], v[26:27]
	v_add_f32_e32 v20, v49, v20
	v_add_f32_e32 v17, v17, v20
	v_add_f32_e32 v16, v16, v17
	s_waitcnt lgkmcnt(0)
	s_nop 1
	v_add_f32_dpp v16, v16, v16 quad_perm:[1,0,3,2] row_mask:0xf bank_mask:0xf
	s_waitcnt lgkmcnt(0)
	s_nop 1
	v_add_f32_dpp v16, v16, v16 quad_perm:[2,3,0,1] row_mask:0xf bank_mask:0xf
	s_waitcnt lgkmcnt(0)
	s_nop 1
	v_add_f32_dpp v16, v16, v16 row_half_mirror row_mask:0xf bank_mask:0xf
	s_waitcnt lgkmcnt(0)
	s_nop 1
	v_add_f32_dpp v16, v16, v16 row_mirror row_mask:0xf bank_mask:0xf
	ds_bpermute_b32 v17, v12, v16
	s_waitcnt lgkmcnt(0)
	v_add_f32_e32 v16, v16, v17
	ds_bpermute_b32 v17, v13, v16
	s_waitcnt lgkmcnt(0)
	v_add_f32_e32 v16, v16, v17
	v_fmamk_f32 v16, v16, 0x3a800000, v175
	v_mul_f32_e32 v17, 0x4f800000, v16
	v_cmp_gt_f32_e32 vcc, s33, v16
	s_nop 1
	v_cndmask_b32_e32 v16, v16, v17, vcc
	v_sqrt_f32_e32 v17, v16
	s_nop 0
	v_add_u32_e32 v20, -1, v17
	v_add_u32_e32 v21, 1, v17
	v_fma_f32 v38, -v20, v17, v16
	v_fma_f32 v39, -v21, v17, v16
	v_cmp_ge_f32_e64 s[40:41], 0, v38
	s_nop 1
	v_cndmask_b32_e64 v17, v17, v20, s[40:41]
	v_cmp_lt_f32_e64 s[40:41], 0, v39
	s_nop 1
	v_cndmask_b32_e64 v17, v17, v21, s[40:41]
	v_mul_f32_e32 v20, 0x37800000, v17
	v_cndmask_b32_e32 v17, v17, v20, vcc
	v_cmp_class_f32_e32 vcc, v16, v180
	s_nop 1
	v_cndmask_b32_e32 v16, v17, v16, vcc
	v_div_scale_f32 v17, s[10:11], v16, v16, 1.0
	v_rcp_f32_e32 v21, v17
	v_div_scale_f32 v20, vcc, 1.0, v16, 1.0
	v_fma_f32 v38, -v17, v21, 1.0
	v_fmac_f32_e32 v21, v38, v21
	v_mul_f32_e32 v38, v20, v21
	v_fma_f32 v39, -v17, v38, v20
	v_fmac_f32_e32 v38, v39, v21
	v_fma_f32 v17, -v17, v38, v20
	v_div_fmas_f32 v17, v17, v21, v38
	v_div_fixup_f32 v20, v17, v16, 1.0
	v_pk_mul_f32 v[28:29], v[20:21], v[28:29] op_sel_hi:[0,1]
	v_pk_mul_f32 v[14:15], v[20:21], v[14:15] op_sel_hi:[0,1]
	v_pk_mul_f32 v[16:17], v[24:25], v[14:15]
	v_pk_mul_f32 v[14:15], v[22:23], v[28:29]
	global_store_dwordx4 v[6:7], v[14:17], off
	s_nop 1
	v_mov_b32_e32 v14, v192
	v_mov_b32_e32 v15, v193
	v_mov_b32_e32 v16, v194
	v_mov_b32_e32 v17, v195
	v_pk_mul_f32 v[22:23], v[20:21], v[32:33] op_sel_hi:[0,1]
	v_pk_mul_f32 v[24:25], v[20:21], v[30:31] op_sel_hi:[0,1]
	v_pk_mul_f32 v[18:19], v[20:21], v[18:19] op_sel_hi:[0,1]
	v_cmp_lt_i32_e32 vcc, s67, v3
	s_or_b64 s[42:43], vcc, s[42:43]
	v_pk_mul_f32 v[14:15], v[14:15], v[24:25]
	v_pk_mul_f32 v[16:17], v[16:17], v[22:23]
	global_store_dwordx4 v[6:7], v[14:17], off offset:16
	s_nop 1
	v_mov_b32_e32 v14, v196
	v_mov_b32_e32 v15, v197
	v_mov_b32_e32 v16, v198
	v_mov_b32_e32 v17, v199
	v_pk_mul_f32 v[22:23], v[20:21], v[34:35] op_sel_hi:[0,1]
	v_pk_mul_f32 v[14:15], v[14:15], v[22:23]
	v_pk_mul_f32 v[16:17], v[16:17], v[18:19]
	global_store_dwordx4 v[6:7], v[14:17], off offset:2048
	s_nop 1
	v_mov_b32_e32 v14, v200
	v_mov_b32_e32 v15, v201
	v_mov_b32_e32 v16, v202
	v_mov_b32_e32 v17, v203
	v_pk_mul_f32 v[18:19], v[20:21], v[36:37] op_sel_hi:[0,1]
	v_pk_mul_f32 v[20:21], v[20:21], v[26:27] op_sel_hi:[0,1]
	v_pk_mul_f32 v[14:15], v[14:15], v[18:19]
	v_pk_mul_f32 v[16:17], v[16:17], v[20:21] op_sel:[0,1] op_sel_hi:[1,0]
	global_store_dwordx4 v[6:7], v[14:17], off offset:2064
	v_lshl_add_u64 v[6:7], v[6:7], 0, s[38:39]
	s_andn2_b64 exec, exec, s[42:43]
	s_cbranch_execnz .LBB0_547
